# hg_sequence: batched LDS reads for stage-O/state-update, cumsum and score chains into free VGPRs with counted lgkmcnt waits
# speedup vs baseline: 1.0079x; 1.0015x over previous
.LBB0_1409:
	v_add_u32_e32 v0, s82, v67
	v_bfe_u32 v62, v58, 16, 1
	s_movk_i32 s26, 0x7fff
	v_add3_u32 v58, v58, v62, s26
	v_mad_u64_u32 v[62:63], s[2:3], v0, s73, v[66:67]
	v_bfe_u32 v0, v59, 16, 1
	v_add3_u32 v0, v59, v0, s26
	ds_write_b16_d16_hi v62, v0 offset:144
	v_bfe_u32 v0, v60, 16, 1
	v_add3_u32 v0, v60, v0, s26
	ds_write_b16_d16_hi v62, v0 offset:288
	v_bfe_u32 v0, v61, 16, 1
	v_add3_u32 v0, v61, v0, s26
	ds_write_b16_d16_hi v62, v0 offset:432
	v_add_u32_e32 v0, s56, v99
	v_mul_lo_u32 v0, v0, s73
	s_add_i32 s2, 0, 0x15200
	v_lshlrev_b32_e32 v94, 4, v100
	v_add3_u32 v0, s2, v0, v94
	s_add_i32 s2, 0, 0x1e200
	v_add_u32_e32 v95, s2, v94
	s_movk_i32 s2, 0x110
	v_lshlrev_b32_e32 v86, 3, v100
	v_mul_lo_u32 v87, v99, s2
	v_add3_u32 v97, 0, v86, v87
	ds_write_b16_d16_hi v62, v58
	v_add_u32_e32 v96, 0x6000, v97
	v_pk_add_f32 v[84:85], v[84:85], v[64:65]
	s_waitcnt lgkmcnt(0)
	s_barrier
	v_cvt_pk_bf16_f32 v78, v50, v51
	v_cvt_pk_bf16_f32 v79, v52, v53
	v_cvt_pk_bf16_f32 v80, v54, v55
	v_cvt_pk_bf16_f32 v81, v56, v57
	v_cvt_pk_bf16_f32 v74, v42, v43
	v_cvt_pk_bf16_f32 v75, v44, v45
	v_cvt_pk_bf16_f32 v76, v46, v47
	v_cvt_pk_bf16_f32 v77, v48, v49
	v_cvt_pk_bf16_f32 v70, v30, v31
	v_cvt_pk_bf16_f32 v71, v32, v33
	v_cvt_pk_bf16_f32 v72, v38, v39
	v_cvt_pk_bf16_f32 v73, v40, v41
	v_cvt_pk_bf16_f32 v66, v26, v27
	v_cvt_pk_bf16_f32 v67, v28, v29
	v_cvt_pk_bf16_f32 v68, v34, v35
	v_cvt_pk_bf16_f32 v69, v36, v37
	ds_read_b128 v[62:65], v0
	ds_read_b128 v[58:61], v0 offset:64
	ds_read2_b64 v[128:131], v96 offset0:128 offset1:132
	ds_read2_b64 v[132:135], v96 offset0:136 offset1:140
	ds_read2_b64 v[136:139], v96 offset0:144 offset1:148
	ds_read2_b64 v[140:143], v96 offset0:152 offset1:156
	v_lshl_add_u32 v0, v100, 12, v99
	v_mul_lo_u32 v96, v99, s73
	v_add_u32_e32 v108, 0x7000, v97
	v_add_u32_e32 v127, v95, v96
	ds_read_b128 v[144:147], v127
	ds_read_b128 v[148:151], v127 offset:64
	ds_read2_b64 v[152:155], v108 offset0:160 offset1:164
	ds_read2_b64 v[156:159], v108 offset0:168 offset1:172
	ds_read2_b64 v[160:163], v108 offset0:176 offset1:180
	ds_read2_b64 v[164:167], v108 offset0:184 offset1:188
	ds_read_b128 v[168:171], v127 offset:2304
	ds_read_b128 v[172:175], v127 offset:2368
	s_mov_b32 s2, 0xfffd0000
	s_waitcnt lgkmcnt(11)
	v_mfma_f32_16x16x32_bf16 v[86:89], v[128:131], v[78:81], 0
	s_waitcnt lgkmcnt(10)
	v_mfma_f32_16x16x32_bf16 v[86:89], v[132:135], v[74:77], v[86:89]
	s_waitcnt lgkmcnt(9)
	v_mfma_f32_16x16x32_bf16 v[86:89], v[136:139], v[70:73], v[86:89]
	s_waitcnt lgkmcnt(8)
	v_mfma_f32_16x16x32_bf16 v[86:89], v[140:143], v[66:69], v[86:89]
	s_waitcnt lgkmcnt(7)
	v_mfma_f32_16x16x32_bf16 v[86:89], v[144:147], v[62:65], v[86:89]
	s_waitcnt lgkmcnt(6)
	v_mfma_f32_16x16x32_bf16 v[100:103], v[148:151], v[58:61], v[86:89]
	v_add_u32_e32 v99, 0x8000, v97
	ds_read2_b64 v[128:131], v99 offset0:192 offset1:196
	ds_read2_b64 v[132:135], v99 offset0:200 offset1:204
	ds_read2_b64 v[136:139], v99 offset0:208 offset1:212
	ds_read2_b64 v[140:143], v99 offset0:216 offset1:220
	ds_read_b128 v[144:147], v127 offset:4608
	ds_read_b128 v[148:151], v127 offset:4672
	v_lshl_add_u64 v[86:87], v[0:1], 2, s[74:75]
	v_add_co_u32_e32 v88, vcc, s2, v86
	s_nop 1
	v_addc_co_u32_e32 v89, vcc, -1, v87, vcc
	global_store_dword v[88:89], v100, off
	v_add_u32_e32 v88, 0x400, v0
	v_mov_b32_e32 v89, v1
	v_lshl_add_u64 v[88:89], v[88:89], 2, s[74:75]
	v_add_co_u32_e32 v90, vcc, s2, v88
	s_nop 1
	v_addc_co_u32_e32 v91, vcc, -1, v89, vcc
	global_store_dword v[90:91], v101, off
	v_add_u32_e32 v90, 0x800, v0
	v_mov_b32_e32 v91, v1
	v_lshl_add_u64 v[90:91], v[90:91], 2, s[74:75]
	v_add_co_u32_e32 v92, vcc, s2, v90
	v_add_u32_e32 v0, 0xc00, v0
	s_nop 0
	v_addc_co_u32_e32 v93, vcc, -1, v91, vcc
	global_store_dword v[92:93], v102, off
	v_lshl_add_u64 v[92:93], v[0:1], 2, s[74:75]
	v_add_co_u32_e32 v100, vcc, s2, v92
	s_nop 1
	v_addc_co_u32_e32 v101, vcc, -1, v93, vcc
	global_store_dword v[100:101], v103, off
	s_mov_b32 s2, 0xfffe0000
	s_waitcnt lgkmcnt(11)
	v_mfma_f32_16x16x32_bf16 v[100:103], v[152:155], v[78:81], 0
	s_waitcnt lgkmcnt(10)
	v_mfma_f32_16x16x32_bf16 v[100:103], v[156:159], v[74:77], v[100:103]
	s_waitcnt lgkmcnt(9)
	v_mfma_f32_16x16x32_bf16 v[100:103], v[160:163], v[70:73], v[100:103]
	s_waitcnt lgkmcnt(8)
	v_mfma_f32_16x16x32_bf16 v[100:103], v[164:167], v[66:69], v[100:103]
	s_waitcnt lgkmcnt(7)
	v_mfma_f32_16x16x32_bf16 v[100:103], v[168:171], v[62:65], v[100:103]
	s_waitcnt lgkmcnt(6)
	v_mfma_f32_16x16x32_bf16 v[100:103], v[172:175], v[58:61], v[100:103]
	v_add_u32_e32 v97, 0x9000, v97
	ds_read2_b64 v[152:155], v97 offset0:224 offset1:228
	ds_read2_b64 v[156:159], v97 offset0:232 offset1:236
	ds_read2_b64 v[160:163], v97 offset0:240 offset1:244
	ds_read2_b64 v[164:167], v97 offset0:248 offset1:252
	ds_read_b128 v[168:171], v127 offset:6912
	ds_read_b128 v[172:175], v127 offset:6976
	v_add_co_u32_e32 v104, vcc, s2, v86
	s_nop 1
	v_addc_co_u32_e32 v105, vcc, -1, v87, vcc
	s_nop 3
	global_store_dword v[104:105], v100, off
	v_add_co_u32_e32 v104, vcc, s2, v88
	s_nop 1
	v_addc_co_u32_e32 v105, vcc, -1, v89, vcc
	v_add_co_u32_e32 v100, vcc, s2, v90
	global_store_dword v[104:105], v101, off
	s_nop 0
	v_addc_co_u32_e32 v101, vcc, -1, v91, vcc
	global_store_dword v[100:101], v102, off
	v_add_co_u32_e32 v100, vcc, s2, v92
	s_nop 1
	v_addc_co_u32_e32 v101, vcc, -1, v93, vcc
	global_store_dword v[100:101], v103, off
	s_mov_b32 s2, 0xffff0000
	s_waitcnt lgkmcnt(11)
	v_mfma_f32_16x16x32_bf16 v[100:103], v[128:131], v[78:81], 0
	s_waitcnt lgkmcnt(10)
	v_mfma_f32_16x16x32_bf16 v[100:103], v[132:135], v[74:77], v[100:103]
	s_waitcnt lgkmcnt(9)
	v_mfma_f32_16x16x32_bf16 v[100:103], v[136:139], v[70:73], v[100:103]
	s_waitcnt lgkmcnt(8)
	v_mfma_f32_16x16x32_bf16 v[100:103], v[140:143], v[66:69], v[100:103]
	s_waitcnt lgkmcnt(7)
	v_mfma_f32_16x16x32_bf16 v[100:103], v[144:147], v[62:65], v[100:103]
	s_waitcnt lgkmcnt(6)
	v_mfma_f32_16x16x32_bf16 v[100:103], v[148:151], v[58:61], v[100:103]
	v_add_u32_e32 v127, 0x19a00, v94
	v_add_u32_e32 v127, v127, v96
	ds_read_b128 v[128:131], v94 offset:6144
	ds_read_b128 v[132:135], v127
	ds_read_b128 v[136:139], v127 offset:64
	ds_read_b128 v[140:143], v94 offset:6208
	ds_read_b128 v[144:147], v127 offset:2304
	ds_read_b128 v[148:151], v127 offset:2368
	v_add_co_u32_e32 v104, vcc, s2, v86
	s_nop 1
	v_addc_co_u32_e32 v105, vcc, -1, v87, vcc
	s_nop 3
	global_store_dword v[104:105], v100, off
	v_add_co_u32_e32 v104, vcc, s2, v88
	s_nop 1
	v_addc_co_u32_e32 v105, vcc, -1, v89, vcc
	v_add_co_u32_e32 v100, vcc, s2, v90
	global_store_dword v[104:105], v101, off
	s_nop 0
	v_addc_co_u32_e32 v101, vcc, -1, v91, vcc
	global_store_dword v[100:101], v102, off
	v_add_co_u32_e32 v100, vcc, s2, v92
	s_nop 1
	v_addc_co_u32_e32 v101, vcc, -1, v93, vcc
	global_store_dword v[100:101], v103, off
	s_add_i32 s2, 0, 0x19a00
	s_waitcnt lgkmcnt(11)
	v_mfma_f32_16x16x32_bf16 v[78:81], v[152:155], v[78:81], 0
	s_add_u32 s34, s34, 0x20000
	s_addc_u32 s35, s35, 0
	s_waitcnt lgkmcnt(10)
	v_mfma_f32_16x16x32_bf16 v[74:77], v[156:159], v[74:77], v[78:81]
	s_add_u32 s74, s74, 0x40000
	s_addc_u32 s75, s75, 0
	s_waitcnt lgkmcnt(9)
	v_mfma_f32_16x16x32_bf16 v[70:73], v[160:163], v[70:73], v[74:77]
	s_cmp_eq_u32 s34, 0x400000
	s_waitcnt lgkmcnt(8)
	v_mfma_f32_16x16x32_bf16 v[66:69], v[164:167], v[66:69], v[70:73]
	s_waitcnt lgkmcnt(7)
	v_mfma_f32_16x16x32_bf16 v[66:69], v[168:171], v[62:65], v[66:69]
	s_waitcnt lgkmcnt(6)
	v_mfma_f32_16x16x32_bf16 v[66:69], v[172:175], v[58:61], v[66:69]
	ds_read_b128 v[152:155], v94 offset:6272
	ds_read_b128 v[156:159], v127 offset:4608
	ds_read_b128 v[160:163], v127 offset:4672
	ds_read_b128 v[164:167], v94 offset:6336
	ds_read_b128 v[168:171], v127 offset:6912
	ds_read_b128 v[172:175], v127 offset:6976
	s_nop 1
	global_store_dword v[86:87], v66, off
	global_store_dword v[88:89], v67, off
	global_store_dword v[90:91], v68, off
	global_store_dword v[92:93], v69, off
	s_waitcnt lgkmcnt(11)
	v_pk_mul_f32 v[50:51], v[50:51], v[128:129]
	v_pk_mul_f32 v[52:53], v[52:53], v[130:131]
	s_waitcnt lgkmcnt(10)
	s_nop 0
	v_mfma_f32_16x16x32_bf16 v[50:53], v[132:135], v[62:65], v[50:53]
	s_waitcnt lgkmcnt(9)
	v_mfma_f32_16x16x32_bf16 v[50:53], v[136:139], v[58:61], v[50:53]
	ds_read_b128 v[128:131], v94 offset:6400
	ds_read_b128 v[132:135], v127 offset:9216
	ds_read_b128 v[136:139], v127 offset:9280
	s_waitcnt lgkmcnt(11)
	v_pk_mul_f32 v[54:55], v[54:55], v[140:141]
	v_pk_mul_f32 v[56:57], v[56:57], v[142:143]
	s_waitcnt lgkmcnt(10)
	s_nop 0
	v_mfma_f32_16x16x32_bf16 v[54:57], v[144:147], v[62:65], v[54:57]
	s_waitcnt lgkmcnt(9)
	v_mfma_f32_16x16x32_bf16 v[54:57], v[148:151], v[58:61], v[54:57]
	ds_read_b128 v[140:143], v94 offset:6464
	ds_read_b128 v[144:147], v127 offset:11520
	ds_read_b128 v[148:151], v127 offset:11584
	s_waitcnt lgkmcnt(11)
	v_pk_mul_f32 v[42:43], v[42:43], v[152:153]
	v_pk_mul_f32 v[44:45], v[44:45], v[154:155]
	s_waitcnt lgkmcnt(10)
	s_nop 0
	v_mfma_f32_16x16x32_bf16 v[42:45], v[156:159], v[62:65], v[42:45]
	s_waitcnt lgkmcnt(9)
	v_mfma_f32_16x16x32_bf16 v[42:45], v[160:163], v[58:61], v[42:45]
	ds_read_b128 v[152:155], v94 offset:6528
	ds_read_b128 v[156:159], v127 offset:13824
	ds_read_b128 v[160:163], v127 offset:13888
	s_waitcnt lgkmcnt(11)
	v_pk_mul_f32 v[46:47], v[46:47], v[164:165]
	v_pk_mul_f32 v[48:49], v[48:49], v[166:167]
	s_waitcnt lgkmcnt(10)
	s_nop 0
	v_mfma_f32_16x16x32_bf16 v[46:49], v[168:171], v[62:65], v[46:49]
	s_waitcnt lgkmcnt(9)
	v_mfma_f32_16x16x32_bf16 v[46:49], v[172:175], v[58:61], v[46:49]
	ds_read_b128 v[164:167], v94 offset:6592
	ds_read_b128 v[168:171], v127 offset:16128
	ds_read_b128 v[172:175], v127 offset:16192
	s_waitcnt lgkmcnt(11)
	v_pk_mul_f32 v[30:31], v[30:31], v[128:129]
	v_pk_mul_f32 v[32:33], v[32:33], v[130:131]
	s_waitcnt lgkmcnt(10)
	s_nop 0
	v_mfma_f32_16x16x32_bf16 v[30:33], v[132:135], v[62:65], v[30:33]
	s_waitcnt lgkmcnt(9)
	v_mfma_f32_16x16x32_bf16 v[30:33], v[136:139], v[58:61], v[30:33]
	s_waitcnt lgkmcnt(8)
	v_pk_mul_f32 v[38:39], v[38:39], v[140:141]
	v_pk_mul_f32 v[40:41], v[40:41], v[142:143]
	s_waitcnt lgkmcnt(7)
	s_nop 0
	v_mfma_f32_16x16x32_bf16 v[38:41], v[144:147], v[62:65], v[38:41]
	s_waitcnt lgkmcnt(6)
	v_mfma_f32_16x16x32_bf16 v[38:41], v[148:151], v[58:61], v[38:41]
	s_waitcnt lgkmcnt(5)
	v_pk_mul_f32 v[26:27], v[26:27], v[152:153]
	v_pk_mul_f32 v[28:29], v[28:29], v[154:155]
	s_waitcnt lgkmcnt(4)
	s_nop 0
	v_mfma_f32_16x16x32_bf16 v[26:29], v[156:159], v[62:65], v[26:29]
	s_waitcnt lgkmcnt(3)
	v_mfma_f32_16x16x32_bf16 v[26:29], v[160:163], v[58:61], v[26:29]
	s_waitcnt lgkmcnt(2)
	v_pk_mul_f32 v[34:35], v[34:35], v[164:165]
	v_pk_mul_f32 v[36:37], v[36:37], v[166:167]
	s_waitcnt lgkmcnt(1)
	s_nop 0
	v_mfma_f32_16x16x32_bf16 v[34:37], v[168:171], v[62:65], v[34:37]
	s_waitcnt lgkmcnt(0)
	s_barrier
	v_mfma_f32_16x16x32_bf16 v[34:37], v[172:175], v[58:61], v[34:37]
	s_cbranch_scc1 .LBB0_1472
.LBB0_1410:
	s_waitcnt vmcnt(38)
	v_lshlrev_b32_e32 v101, 16, v16
	v_sub_f32_e32 v58, 1.0, v101
	v_max_f32_e32 v58, 0x3a800000, v58
	s_mov_b32 s2, 0x800000
	s_mov_b32 s3, 0x3f317217
	s_mov_b32 s28, 0x7f800000
	v_log_f32_e32 v58, v58
	v_and_b32_e32 v104, 0xffff0000, v16
	s_waitcnt vmcnt(36)
	v_lshlrev_b32_e32 v102, 16, v17
	v_and_b32_e32 v105, 0xffff0000, v17
	v_mul_f32_e32 v59, 0x3f317217, v58
	v_fma_f32 v59, v58, s3, -v59
	v_fmac_f32_e32 v59, 0x3377d1cf, v58
	v_fmac_f32_e32 v59, 0x3f317217, v58
	s_waitcnt vmcnt(32)
	v_lshlrev_b32_e32 v103, 16, v18
	v_and_b32_e32 v107, 0xffff0000, v18
	v_mov_b32_e32 v58, v59

	v_sub_f32_e32 v59, 1.0, v104
	v_max_f32_e32 v59, 0x3a800000, v59
	s_waitcnt vmcnt(30)
	v_lshlrev_b32_e32 v106, 16, v19
	v_and_b32_e32 v109, 0xffff0000, v19
	v_log_f32_e32 v59, v59
	s_waitcnt vmcnt(26)
	v_lshlrev_b32_e32 v108, 16, v20
	v_and_b32_e32 v112, 0xffff0000, v20
	s_waitcnt vmcnt(24)
	v_lshlrev_b32_e32 v110, 16, v21
	v_mul_f32_e32 v60, 0x3f317217, v59
	v_fma_f32 v60, v59, s3, -v60
	v_fmac_f32_e32 v60, 0x3377d1cf, v59
	v_fmac_f32_e32 v60, 0x3f317217, v59
	v_and_b32_e32 v114, 0xffff0000, v21
	s_waitcnt vmcnt(19)
	v_lshlrev_b32_e32 v113, 16, v22
	v_mov_b32_e32 v59, v60

	v_pk_add_f32 v[62:63], v[58:59], 0 op_sel_hi:[1,0]
	v_sub_f32_e32 v58, 1.0, v102
	v_max_f32_e32 v58, 0x3a800000, v58
	v_and_b32_e32 v116, 0xffff0000, v22
	s_waitcnt vmcnt(18)
	v_lshlrev_b32_e32 v115, 16, v23
	v_log_f32_e32 v58, v58
	v_and_b32_e32 v117, 0xffff0000, v23
	v_mov_b32_e32 v99, v83
	v_mov_b32_e32 v0, v82
	v_mul_f32_e32 v59, 0x3f317217, v58
	v_fma_f32 v59, v58, s3, -v59
	v_fmac_f32_e32 v59, 0x3377d1cf, v58
	v_fmac_f32_e32 v59, 0x3f317217, v58
	v_mov_b32_e32 v100, v98

	v_mov_b32_e32 v58, v59

	v_sub_f32_e32 v59, 1.0, v105
	v_max_f32_e32 v59, 0x3a800000, v59

	v_log_f32_e32 v59, v59
	s_nop 0
	v_mul_f32_e32 v60, 0x3f317217, v59
	v_fma_f32 v60, v59, s3, -v60
	v_fmac_f32_e32 v60, 0x3377d1cf, v59
	v_fmac_f32_e32 v60, 0x3f317217, v59

	v_mov_b32_e32 v59, v60

	v_sub_f32_e32 v60, 1.0, v103
	v_max_f32_e32 v60, 0x3a800000, v60
	v_pk_add_f32 v[58:59], v[58:59], v[62:63]

	v_log_f32_e32 v60, v60
	s_nop 0
	v_mul_f32_e32 v61, 0x3f317217, v60
	v_fma_f32 v61, v60, s3, -v61
	v_fmac_f32_e32 v61, 0x3377d1cf, v60
	v_fmac_f32_e32 v61, 0x3f317217, v60

	v_mov_b32_e32 v60, v61

	v_sub_f32_e32 v61, 1.0, v107
	v_max_f32_e32 v61, 0x3a800000, v61

	v_log_f32_e32 v61, v61
	s_nop 0
	v_mul_f32_e32 v64, 0x3f317217, v61
	v_fma_f32 v64, v61, s3, -v64
	v_fmac_f32_e32 v64, 0x3377d1cf, v61
	v_fmac_f32_e32 v64, 0x3f317217, v61
	s_nop 1
	v_mov_b32_e32 v61, v64

	v_sub_f32_e32 v64, 1.0, v106
	v_max_f32_e32 v64, 0x3a800000, v64
	v_pk_add_f32 v[60:61], v[60:61], v[58:59]

	v_log_f32_e32 v64, v64
	s_nop 0
	v_mul_f32_e32 v65, 0x3f317217, v64
	v_fma_f32 v65, v64, s3, -v65
	v_fmac_f32_e32 v65, 0x3377d1cf, v64
	v_fmac_f32_e32 v65, 0x3f317217, v64
	s_nop 1
	v_mov_b32_e32 v64, v65

	v_sub_f32_e32 v65, 1.0, v109
	v_max_f32_e32 v65, 0x3a800000, v65

	v_log_f32_e32 v65, v65
	s_nop 0
	v_mul_f32_e32 v66, 0x3f317217, v65
	v_fma_f32 v66, v65, s3, -v66
	v_fmac_f32_e32 v66, 0x3377d1cf, v65
	v_fmac_f32_e32 v66, 0x3f317217, v65
	s_nop 1
	v_mov_b32_e32 v65, v66

	v_pk_add_f32 v[66:67], v[64:65], v[60:61]
	v_sub_f32_e32 v64, 1.0, v108
	v_max_f32_e32 v64, 0x3a800000, v64

	v_log_f32_e32 v64, v64
	s_nop 0
	v_mul_f32_e32 v65, 0x3f317217, v64
	v_fma_f32 v65, v64, s3, -v65
	v_fmac_f32_e32 v65, 0x3377d1cf, v64
	v_fmac_f32_e32 v65, 0x3f317217, v64
	s_nop 1
	v_mov_b32_e32 v64, v65

	v_sub_f32_e32 v65, 1.0, v112
	v_max_f32_e32 v65, 0x3a800000, v65

	v_log_f32_e32 v65, v65
	s_nop 0
	v_mul_f32_e32 v68, 0x3f317217, v65
	v_fma_f32 v68, v65, s3, -v68
	v_fmac_f32_e32 v68, 0x3377d1cf, v65
	v_fmac_f32_e32 v68, 0x3f317217, v65
	s_nop 1
	v_mov_b32_e32 v65, v68

	v_pk_add_f32 v[68:69], v[64:65], v[66:67]
	v_sub_f32_e32 v64, 1.0, v110
	v_max_f32_e32 v64, 0x3a800000, v64

	v_log_f32_e32 v64, v64
	s_nop 0
	v_mul_f32_e32 v65, 0x3f317217, v64
	v_fma_f32 v65, v64, s3, -v65
	v_fmac_f32_e32 v65, 0x3377d1cf, v64
	v_fmac_f32_e32 v65, 0x3f317217, v64
	s_nop 1
	v_mov_b32_e32 v64, v65

	v_sub_f32_e32 v65, 1.0, v114
	v_max_f32_e32 v65, 0x3a800000, v65

	v_log_f32_e32 v65, v65
	s_nop 0
	v_mul_f32_e32 v70, 0x3f317217, v65
	v_fma_f32 v70, v65, s3, -v70
	v_fmac_f32_e32 v70, 0x3377d1cf, v65
	v_fmac_f32_e32 v70, 0x3f317217, v65
	s_nop 1
	v_mov_b32_e32 v65, v70

	v_pk_add_f32 v[70:71], v[64:65], v[68:69]
	v_sub_f32_e32 v64, 1.0, v113
	v_max_f32_e32 v64, 0x3a800000, v64

	v_log_f32_e32 v64, v64
	s_nop 0
	v_mul_f32_e32 v65, 0x3f317217, v64
	v_fma_f32 v65, v64, s3, -v65
	v_fmac_f32_e32 v65, 0x3377d1cf, v64
	v_fmac_f32_e32 v65, 0x3f317217, v64
	s_nop 1
	v_mov_b32_e32 v64, v65

	v_sub_f32_e32 v65, 1.0, v116
	v_max_f32_e32 v65, 0x3a800000, v65

	v_log_f32_e32 v65, v65
	s_nop 0
	v_mul_f32_e32 v72, 0x3f317217, v65
	v_fma_f32 v72, v65, s3, -v72
	v_fmac_f32_e32 v72, 0x3377d1cf, v65
	v_fmac_f32_e32 v72, 0x3f317217, v65
	s_nop 1
	v_mov_b32_e32 v65, v72

	v_pk_add_f32 v[72:73], v[64:65], v[70:71]
	v_sub_f32_e32 v64, 1.0, v115
	v_max_f32_e32 v64, 0x3a800000, v64

	v_log_f32_e32 v64, v64
	s_nop 0
	v_mul_f32_e32 v65, 0x3f317217, v64
	v_fma_f32 v65, v64, s3, -v65
	v_fmac_f32_e32 v65, 0x3377d1cf, v64
	v_fmac_f32_e32 v65, 0x3f317217, v64
	s_nop 1
	v_mov_b32_e32 v64, v65

	v_sub_f32_e32 v65, 1.0, v117
	v_max_f32_e32 v65, 0x3a800000, v65

	v_log_f32_e32 v65, v65
	s_nop 0
	v_mul_f32_e32 v74, 0x3f317217, v65
	v_fma_f32 v74, v65, s3, -v74
	v_fmac_f32_e32 v74, 0x3377d1cf, v65
	v_fmac_f32_e32 v74, 0x3f317217, v65
	s_nop 1
	v_mov_b32_e32 v65, v74

	v_pk_add_f32 v[74:75], v[64:65], v[72:73]
	v_lshlrev_b32_e32 v64, 2, v0
	v_add_u32_e32 v65, s76, v64
	ds_write_b64 v65, v[74:75]
	s_waitcnt lgkmcnt(0)
	s_barrier
	v_add_u32_e32 v111, 0, v64
	ds_read2st64_b64 v[76:79], v111 offset1:1
	ds_read2st64_b64 v[128:131], v111 offset0:2 offset1:3
	ds_read2st64_b64 v[132:135], v111 offset0:4 offset1:5
	ds_read2st64_b64 v[136:139], v111 offset0:6 offset1:7
	s_andn2_b64 vcc, exec, s[58:59]
	s_waitcnt lgkmcnt(3)
	v_pk_add_f32 v[64:65], v[76:77], 0 op_sel_hi:[1,0]
	s_nop 0
	v_pk_add_f32 v[80:81], v[64:65], v[78:79]
	v_cndmask_b32_e64 v86, 0, v65, s[10:11]
	v_cndmask_b32_e64 v87, 0, v64, s[10:11]
	s_waitcnt lgkmcnt(2)
	v_pk_add_f32 v[64:65], v[80:81], v[128:129]
	v_cndmask_b32_e64 v76, v87, v80, s[12:13]
	v_cndmask_b32_e64 v77, v86, v81, s[12:13]
	v_cndmask_b32_e64 v86, v77, v65, s[14:15]
	v_cndmask_b32_e64 v87, v76, v64, s[14:15]
	v_pk_add_f32 v[94:95], v[64:65], v[130:131]
	s_waitcnt lgkmcnt(1)
	v_pk_add_f32 v[64:65], v[94:95], v[132:133]
	v_cndmask_b32_e64 v76, v87, v94, s[16:17]
	v_cndmask_b32_e64 v77, v86, v95, s[16:17]
	v_cndmask_b32_e64 v77, v77, v65, s[18:19]
	v_cndmask_b32_e64 v76, v76, v64, s[18:19]
	v_pk_add_f32 v[96:97], v[64:65], v[134:135]
	s_nop 0
	v_cndmask_b32_e64 v88, v76, v96, s[20:21]
	v_cndmask_b32_e64 v89, v77, v97, s[20:21]
	s_waitcnt lgkmcnt(0)
	v_pk_add_f32 v[86:87], v[96:97], v[136:137]
	s_nop 0
	v_pk_add_f32 v[64:65], v[86:87], v[138:139]
	v_cndmask_b32_e64 v76, 0, v81, s[8:9]
	v_cndmask_b32_e64 v77, 0, v80, s[8:9]
	v_cndmask_b32_e64 v78, v81, v95, s[8:9]
	v_cndmask_b32_e64 v79, v80, v94, s[8:9]
	v_cndmask_b32_e64 v77, v77, v94, s[6:7]
	v_cndmask_b32_e64 v76, v76, v95, s[6:7]
	v_cndmask_b32_e64 v79, v79, v96, s[6:7]
	v_cndmask_b32_e64 v78, v78, v97, s[6:7]
	v_cndmask_b32_e64 v91, v76, v97, s[24:25]
	v_cndmask_b32_e64 v90, v77, v96, s[24:25]
	v_cndmask_b32_e64 v77, v78, v65, s[24:25]
	v_cndmask_b32_e64 v76, v79, v64, s[24:25]
	v_pk_add_f32 v[78:79], v[80:81], v[76:77] neg_lo:[0,1] neg_hi:[0,1]
	v_mul_f32_e32 v92, 0x3fb8aa3b, v90
	v_min_f32_e32 v78, 0, v78
	v_mul_f32_e32 v78, 0x3fb8aa3b, v78
	v_exp_f32_e32 v118, v78
	v_min_f32_e32 v78, 0, v79
	v_mul_f32_e32 v78, 0x3fb8aa3b, v78
	v_exp_f32_e32 v119, v78
	v_cndmask_b32_e64 v79, v89, v87, s[22:23]
	v_cndmask_b32_e64 v78, v88, v86, s[22:23]
	v_pk_add_f32 v[88:89], v[78:79], v[90:91] neg_lo:[0,1] neg_hi:[0,1]
	v_mul_f32_e32 v93, 0x3fb8aa3b, v91
	v_pk_add_f32 v[62:63], v[62:63], v[88:89]
	v_pk_add_f32 v[86:87], v[76:77], v[90:91] neg_lo:[0,1] neg_hi:[0,1]
	v_mul_f32_e32 v90, 0x3fb8aa3b, v62
	v_exp_f32_e32 v78, v93
	v_exp_f32_e32 v93, v90
	v_mul_f32_e32 v90, 0x3fb8aa3b, v63
	v_exp_f32_e32 v123, v90
	v_mul_f32_e32 v79, 0x3fb8aa3b, v84
	v_rcp_f32_e32 v90, v93
	v_exp_f32_e32 v80, v92
	v_exp_f32_e32 v92, v79
	v_mul_f32_e32 v79, 0x3fb8aa3b, v85
	v_exp_f32_e32 v122, v79
	v_min_f32_e32 v121, 0x79297b5a, v90
	v_rcp_f32_e32 v90, v123
	v_pk_add_f32 v[62:63], v[86:87], v[62:63] neg_lo:[0,1] neg_hi:[0,1]
	v_lshlrev_b32_e32 v79, 1, v0
	v_mul_f32_e32 v62, 0x3fb8aa3b, v62
	v_sub_u32_e32 v120, v111, v79
	v_lshlrev_b32_e32 v81, 16, v8
	v_and_b32_e32 v79, 0xffff0000, v8
	v_exp_f32_e32 v125, v62
	v_mul_f32_e32 v62, 0x3fb8aa3b, v63
	v_min_f32_e32 v124, 0x79297b5a, v90
	v_exp_f32_e32 v126, v62
	v_pk_mul_f32 v[90:91], v[92:93], v[80:81]
	v_pk_mul_f32 v[92:93], v[122:123], v[78:79]
	v_lshl_add_u32 v63, s39, 1, v120
	v_cvt_pk_bf16_f32 v62, v91, v93
	ds_write_b32 v63, v62 offset:8192
	v_mul_f32_e32 v62, v80, v91
	v_mul_f32_e32 v79, v78, v93
	v_cvt_pk_bf16_f32 v62, v62, v79
	ds_write_b32 v63, v62 offset:25600
	v_mul_f32_e32 v62, v90, v91
	v_mul_f32_e32 v63, v92, v93
	v_cvt_pk_bf16_f32 v79, v62, v63
	v_lshl_add_u64 v[62:63], v[0:1], 1, s[34:35]
	v_lshl_add_u64 v[122:123], s[52:53], 0, v[62:63]
	v_mul_f32_e32 v91, v121, v101
	v_mul_f32_e32 v93, v124, v104
	global_store_dword v[122:123], v79, off
	v_cvt_pk_bf16_f32 v91, v91, v93
	v_add_u32_e32 v93, s38, v120
	ds_write_b32 v93, v91 offset:43008
	v_cndmask_b32_e64 v91, 0, 1, s[58:59]
	v_mul_f32_e32 v79, v125, v101
	v_mul_f32_e32 v81, v126, v104
	v_cmp_ne_u32_e64 s[26:27], 1, v91
	v_add_u32_e32 v101, s33, v120
	s_cbranch_vccnz .LBB0_1412
	v_mul_f32_e32 v91, v119, v81
	v_mul_f32_e32 v93, v118, v79
	v_cvt_pk_bf16_f32 v91, v93, v91
	ds_write_b32 v101, v91 offset:47360

.LBB0_1446:
	s_waitcnt lgkmcnt(0)
	s_barrier
	s_andn2_b64 vcc, exec, s[64:65]
	s_cbranch_vccnz .Lc1_noread
	s_movk_i32 s26, 0x110
	v_readlane_b32 s2, v254, 49
	v_add_u32_e32 v160, s86, v99
	v_lshlrev_b32_e32 v161, 4, v100
	v_mul_lo_u32 v162, v160, s26
	v_add_u32_e32 v160, s88, v99
	v_add_u32_e32 v160, s2, v160
	v_mul_lo_u32 v163, v160, s26
	v_add_u32_e32 v162, v162, v161
	v_add_u32_e32 v163, v163, v161
	ds_read_b128 v[128:131], v162 offset:8192
	ds_read_b128 v[132:135], v163 offset:43008
	ds_read_b128 v[136:139], v162 offset:8256
	ds_read_b128 v[140:143], v163 offset:43072
	ds_read_b128 v[144:147], v162 offset:8320
	ds_read_b128 v[148:151], v163 offset:43136
	ds_read_b128 v[152:155], v162 offset:8384
	ds_read_b128 v[156:159], v163 offset:43200
.Lc1_noread:
	s_cmp_eq_u32 s34, 0x3e0000
	s_cbranch_scc1 .LBB0_1466
	s_andn2_b64 vcc, exec, s[36:37]
	s_mov_b64 s[2:3], -1
	s_cbranch_vccnz .LBB0_1449
	s_mov_b64 s[2:3], 0

.LBB0_1466:
	v_lshlrev_b32_e32 v67, 2, v100
	v_lshl_add_u32 v0, v100, 4, 0
	v_add_u32_e32 v68, s88, v99
	v_mov_b32_e32 v58, 0
	s_andn2_b64 vcc, exec, s[64:65]
	v_mov_b32_e32 v60, 0
	v_mov_b32_e32 v61, 0
	v_mov_b32_e32 v62, 0
	v_mov_b32_e32 v63, 0
	s_cbranch_vccnz .LBB0_1469
	v_readlane_b32 s2, v254, 51
	v_readlane_b32 s3, v254, 52
	s_waitcnt lgkmcnt(6)
	v_mfma_f32_16x16x32_bf16 v[60:63], v[128:131], v[132:135], 0
	s_andn2_b64 vcc, exec, s[2:3]
	s_waitcnt lgkmcnt(4)
	v_mfma_f32_16x16x32_bf16 v[60:63], v[136:139], v[140:143], v[60:63]
	s_waitcnt lgkmcnt(2)
	v_mfma_f32_16x16x32_bf16 v[60:63], v[144:147], v[148:151], v[60:63]
	s_waitcnt lgkmcnt(0)
	v_mfma_f32_16x16x32_bf16 v[60:63], v[152:155], v[156:159], v[60:63]
	s_cbranch_vccnz .LBB0_1469
	v_cmp_le_i32_e32 vcc, v99, v67
	v_or_b32_e32 v59, 1, v67
	s_nop 4
	v_cndmask_b32_e32 v60, 0, v60, vcc
	v_cmp_le_i32_e32 vcc, v99, v59
	v_or_b32_e32 v59, 2, v67
	s_nop 0
	v_cndmask_b32_e32 v61, 0, v61, vcc
	v_cmp_le_i32_e32 vcc, v99, v59
	v_or_b32_e32 v59, 3, v67
	s_nop 0
	v_cndmask_b32_e32 v62, 0, v62, vcc
	v_cmp_le_i32_e32 vcc, v99, v59
	s_nop 1
	v_cndmask_b32_e32 v63, 0, v63, vcc
.LBB0_1469:
	s_andn2_b64 vcc, exec, s[70:71]
	s_cbranch_vccnz .Lc2_noread
	s_movk_i32 s26, 0x110
	v_readlane_b32 s2, v254, 53
	v_add_u32_e32 v160, s82, v99
	v_mul_lo_u32 v162, v160, s26
	v_add_u32_e32 v160, s2, v68
	v_mul_lo_u32 v163, v160, s26
	v_add_u32_e32 v162, v162, v0
	v_add_u32_e32 v163, v163, v0
	ds_read_b128 v[128:131], v162 offset:8192
	ds_read_b128 v[132:135], v163 offset:43008
	ds_read_b128 v[136:139], v162 offset:8256
	ds_read_b128 v[140:143], v163 offset:43072
	ds_read_b128 v[144:147], v162 offset:8320
	ds_read_b128 v[148:151], v163 offset:43136
	ds_read_b128 v[152:155], v162 offset:8384
	ds_read_b128 v[156:159], v163 offset:43200
.Lc2_noread:
	v_lshl_add_u32 v66, v99, 1, s77
	v_add_u32_e32 v59, s86, v67
	s_movk_i32 s26, 0x7fff
	v_mad_u64_u32 v[70:71], s[2:3], v59, s73, v[66:67]
	s_nop 2
	v_bfe_u32 v59, v61, 16, 1
	v_add3_u32 v59, v61, v59, s26
	ds_write_b16_d16_hi v70, v59 offset:144
	v_bfe_u32 v59, v62, 16, 1
	v_add3_u32 v59, v62, v59, s26
	v_bfe_u32 v69, v60, 16, 1
	ds_write_b16_d16_hi v70, v59 offset:288
	v_bfe_u32 v59, v63, 16, 1
	v_add3_u32 v60, v60, v69, s26
	v_add3_u32 v59, v63, v59, s26
	ds_write_b16_d16_hi v70, v60
	ds_write_b16_d16_hi v70, v59 offset:432
	s_andn2_b64 vcc, exec, s[70:71]
	v_mov_b32_e32 v59, 0
	v_mov_b32_e32 v60, 0
	v_mov_b32_e32 v61, 0
	s_cbranch_vccnz .LBB0_1409
	v_readlane_b32 s2, v254, 54
	v_readlane_b32 s3, v254, 55
	s_waitcnt lgkmcnt(10)
	v_mfma_f32_16x16x32_bf16 v[58:61], v[128:131], v[132:135], 0
	s_andn2_b64 vcc, exec, s[2:3]
	s_waitcnt lgkmcnt(8)
	v_mfma_f32_16x16x32_bf16 v[58:61], v[136:139], v[140:143], v[58:61]
	s_waitcnt lgkmcnt(6)
	v_mfma_f32_16x16x32_bf16 v[58:61], v[144:147], v[148:151], v[58:61]
	s_waitcnt lgkmcnt(4)
	v_mfma_f32_16x16x32_bf16 v[58:61], v[152:155], v[156:159], v[58:61]
	s_cbranch_vccnz .LBB0_1409
	v_cmp_le_i32_e32 vcc, v99, v67
	v_or_b32_e32 v0, 1, v67
	s_nop 4
	v_cndmask_b32_e32 v58, 0, v58, vcc
	v_cmp_le_i32_e32 vcc, v99, v0
	v_or_b32_e32 v0, 2, v67
	s_nop 0
	v_cndmask_b32_e32 v59, 0, v59, vcc
	v_cmp_le_i32_e32 vcc, v99, v0
	v_or_b32_e32 v0, 3, v67
	s_nop 0
	v_cndmask_b32_e32 v60, 0, v60, vcc
	v_cmp_le_i32_e32 vcc, v99, v0
	s_nop 1
	v_cndmask_b32_e32 v61, 0, v61, vcc
	s_branch .LBB0_1409

.LBB0_1497:
	v_readlane_b32 s4, v254, 15
	v_readlane_b32 s6, v254, 27
	v_readlane_b32 s5, v254, 16
	v_readlane_b32 s7, v254, 28
	s_add_u32 s4, s6, s4
	s_addc_u32 s5, s7, s5
	v_readlane_b32 s6, v254, 29
	v_cvt_pk_bf16_f32 v2, v2, v3
	v_cvt_pk_bf16_f32 v3, v32, v33
	v_cvt_pk_bf16_f32 v4, v4, v5
	v_cvt_pk_bf16_f32 v5, v30, v31
	v_cvt_pk_bf16_f32 v6, v6, v7
	v_cvt_pk_bf16_f32 v7, v28, v29
	v_cvt_pk_bf16_f32 v8, v8, v9
	v_cvt_pk_bf16_f32 v9, v26, v27
	v_cvt_pk_bf16_f32 v10, v10, v11
	v_cvt_pk_bf16_f32 v11, v24, v25
	v_cvt_pk_bf16_f32 v12, v12, v13
	v_cvt_pk_bf16_f32 v13, v22, v23
	v_cvt_pk_bf16_f32 v14, v14, v15
	v_cvt_pk_bf16_f32 v15, v20, v21
	v_cvt_pk_bf16_f32 v16, v16, v17
	v_cvt_pk_bf16_f32 v17, v18, v19
	v_or_b32_e32 v18, s8, v186
	v_readlane_b32 s12, v254, 35
	v_readlane_b32 s7, v254, 30
	s_add_u32 s19, s6, 0x54100000
	v_ashrrev_i32_e32 v19, 31, v18
	v_readlane_b32 s13, v254, 36
	s_addc_u32 s20, s7, 0
	v_lshl_add_u64 v[18:19], v[18:19], 2, s[4:5]
	s_lshl_b64 s[4:5], s[12:13], 11
	v_readlane_b32 s30, v254, 25
	v_readlane_b32 s31, v254, 26
	s_add_u32 s6, s30, s4
	v_readlane_b32 s10, v254, 37
	s_addc_u32 s7, s31, s5
	s_lshl_b32 s21, s10, 1
	v_readlane_b32 s11, v254, 38
	s_mov_b32 s14, s10
	s_add_u32 s10, s6, s21
	s_addc_u32 s11, s7, 0
	s_lshl_b64 s[6:7], s[8:9], 1
	s_add_u32 s10, s10, s6
	s_addc_u32 s11, s11, s7
	s_add_u32 s10, s10, 0x33900000
	s_addc_u32 s11, s11, 0
	s_lshl_b64 s[12:13], s[12:13], 12
	s_add_u32 s12, s0, s12
	s_addc_u32 s13, s1, s13
	s_lshl_b32 s14, s14, 2
	s_add_u32 s12, s12, s14
	s_addc_u32 s13, s13, 0
	s_lshl_b64 s[8:9], s[8:9], 2
	s_add_u32 s12, s12, s8
	s_addc_u32 s13, s13, s9
	s_add_u32 s12, s12, 0x6cb00000
	s_addc_u32 s13, s13, 0
	s_add_u32 s14, s2, s21
	v_lshl_or_b32 v0, v187, 12, v186
	v_lshl_or_b32 v98, v56, 10, v186
	v_mov_b32_e32 v99, v1
	global_load_dword v188, v[18:19], off
	s_addc_u32 s15, s3, 0
	v_lshlrev_b32_e32 v154, 2, v0
	v_lshl_add_u64 v[18:19], v[98:99], 2, s[12:13]
	v_lshl_or_b32 v100, v55, 10, v186
	v_mov_b32_e32 v101, v1
	v_lshl_or_b32 v102, v54, 10, v186
	v_mov_b32_e32 v103, v1
	v_lshl_add_u64 v[20:21], v[100:101], 2, s[12:13]
	v_lshl_add_u64 v[22:23], v[102:103], 2, s[12:13]
	global_load_dword v54, v154, s[12:13]
	global_load_dword v55, v[18:19], off
	global_load_dword v56, v[20:21], off
	global_load_dword v57, v[22:23], off
	s_add_u32 s14, s14, s4
	v_lshlrev_b32_e32 v18, 1, v40
	s_addc_u32 s15, s15, s5
	v_lshl_or_b32 v114, v186, 11, v18
	v_mov_b32_e32 v115, v1
	v_lshl_add_u64 v[18:19], s[14:15], 0, v[114:115]
	s_mov_b64 s[16:17], 0x5c300000
	v_lshl_add_u64 v[20:21], v[18:19], 0, s[16:17]
	s_mov_b32 s16, 0x5c300000
	v_add_co_u32_e32 v18, vcc, s16, v18
	s_add_u32 s16, s14, 0x5c308000
	v_lshl_or_b32 v104, v65, 10, v186
	v_mov_b32_e32 v105, v1
	v_lshl_or_b32 v166, v63, 10, v186
	v_mov_b32_e32 v167, v1
	v_lshl_or_b32 v168, v62, 10, v186
	v_mov_b32_e32 v169, v1
	s_addc_u32 s17, s15, 0
	v_lshl_or_b32 v170, v61, 10, v186
	v_mov_b32_e32 v171, v1
	v_lshl_or_b32 v172, v60, 10, v186
	v_mov_b32_e32 v173, v1
	v_lshlrev_b32_e32 v108, 1, v98
	v_addc_co_u32_e32 v19, vcc, 0, v19, vcc
	v_lshl_add_u64 v[22:23], v[104:105], 2, s[12:13]
	v_lshl_or_b32 v106, v64, 10, v186
	v_mov_b32_e32 v107, v1
	v_lshl_add_u64 v[28:29], v[166:167], 2, s[12:13]
	v_lshl_add_u64 v[30:31], v[168:169], 2, s[12:13]
	v_lshl_add_u64 v[32:33], v[170:171], 2, s[12:13]
	v_lshl_add_u64 v[36:37], v[172:173], 2, s[12:13]
	v_lshl_or_b32 v174, v53, 10, v186
	v_mov_b32_e32 v175, v1
	v_lshl_or_b32 v176, v52, 10, v186
	v_mov_b32_e32 v177, v1
	s_add_u32 s24, s14, 0x5c310000
	v_lshl_or_b32 v178, v59, 10, v186
	v_mov_b32_e32 v179, v1
	v_lshlrev_b32_e32 v0, 1, v0
	v_lshlrev_b32_e32 v110, 1, v100
	v_lshlrev_b32_e32 v112, 1, v102
	global_load_dwordx2 v[96:97], v[20:21], off offset:32
	global_load_dwordx2 v[90:91], v[20:21], off offset:64
	global_load_dwordx2 v[92:93], v[20:21], off offset:96
	global_load_dwordx2 v[38:39], v[20:21], off offset:128
	global_load_dwordx2 v[94:95], v[18:19], off
	global_load_dwordx2 v[40:41], v[20:21], off offset:160
	s_nop 0
	global_load_dwordx2 v[18:19], v[20:21], off offset:192
	s_nop 0
	global_load_dwordx2 v[20:21], v[20:21], off offset:224
	v_lshlrev_b32_e32 v130, 1, v104
	v_lshl_add_u64 v[24:25], v[106:107], 2, s[12:13]
	v_lshlrev_b32_e32 v132, 1, v106
	v_lshlrev_b32_e32 v134, 1, v166
	v_lshlrev_b32_e32 v136, 1, v168
	v_or_b32_e32 v116, 64, v114
	v_lshlrev_b32_e32 v138, 1, v170
	global_load_ushort v219, v108, s[10:11]
	global_load_ushort v218, v110, s[10:11]
	global_load_ushort v217, v112, s[10:11]
	global_load_ushort v216, v130, s[10:11]
	global_load_ushort v215, v132, s[10:11]
	global_load_ushort v214, v134, s[10:11]
	global_load_ushort v212, v136, s[10:11]
	global_load_ushort v210, v138, s[10:11]
	v_lshl_add_u64 v[42:43], v[174:175], 2, s[12:13]
	v_lshl_add_u64 v[44:45], v[176:177], 2, s[12:13]
	global_load_dword v26, v[22:23], off
	global_load_dword v27, v[24:25], off
	s_nop 0
	global_load_dword v28, v[28:29], off
	s_nop 0
	global_load_dword v29, v[30:31], off
	s_nop 0
	global_load_dword v30, v[32:33], off
	global_load_dword v31, v[36:37], off
	s_nop 0
	global_load_dword v32, v[42:43], off
	global_load_dword v33, v[44:45], off
	s_addc_u32 s25, s15, 0
	v_lshl_add_u64 v[36:37], v[178:179], 2, s[12:13]
	v_lshl_or_b32 v180, v58, 10, v186
	v_mov_b32_e32 v181, v1
	v_lshl_or_b32 v182, v35, 10, v186
	v_mov_b32_e32 v183, v1
	v_lshl_or_b32 v184, v34, 10, v186
	v_mov_b32_e32 v185, v1
	v_or_b32_e32 v120, 0xc0, v114
	v_lshlrev_b32_e32 v140, 1, v172
	v_lshlrev_b32_e32 v142, 1, v174
	v_lshlrev_b32_e32 v144, 1, v176
	global_load_dwordx2 v[50:51], v116, s[16:17]
	global_load_dwordx2 v[52:53], v116, s[16:17] offset:32
	global_load_dwordx2 v[46:47], v116, s[24:25]
	global_load_dwordx2 v[48:49], v116, s[24:25] offset:32
	global_load_dwordx2 v[42:43], v120, s[16:17]
	global_load_dwordx2 v[44:45], v120, s[16:17] offset:32
	global_load_dwordx2 v[22:23], v120, s[24:25]
	global_load_dwordx2 v[24:25], v120, s[24:25] offset:32
	v_lshlrev_b32_e32 v146, 1, v178
	v_lshl_add_u64 v[58:59], v[180:181], 2, s[12:13]
	v_lshlrev_b32_e32 v148, 1, v180
	v_lshl_add_u64 v[60:61], v[182:183], 2, s[12:13]
	v_lshlrev_b32_e32 v150, 1, v182
	v_lshl_add_u64 v[62:63], v[184:185], 2, s[12:13]
	global_load_dword v34, v[36:37], off
	global_load_dword v35, v[58:59], off
	s_nop 0
	global_load_dword v36, v[60:61], off
	global_load_dword v37, v[62:63], off
	v_lshlrev_b32_e32 v152, 1, v184
	global_load_ushort v221, v0, s[10:11]
	global_load_ushort v213, v140, s[10:11]
	global_load_ushort v211, v142, s[10:11]
	global_load_ushort v209, v144, s[10:11]
	global_load_ushort v208, v146, s[10:11]
	global_load_ushort v207, v148, s[10:11]
	global_load_ushort v206, v150, s[10:11]
	global_load_ushort v205, v152, s[10:11]
	s_add_u32 s10, s14, 0x5c318000
	v_or_b32_e32 v118, 0x80, v114
	s_addc_u32 s11, s15, 0
	global_load_dwordx2 v[78:79], v114, s[24:25]
	global_load_dwordx2 v[80:81], v114, s[24:25] offset:32
	global_load_dwordx2 v[62:63], v114, s[10:11]
	global_load_dwordx2 v[64:65], v114, s[10:11] offset:32
	global_load_dwordx2 v[86:87], v114, s[16:17]
	global_load_dwordx2 v[88:89], v114, s[16:17] offset:32
	global_load_dwordx2 v[58:59], v116, s[10:11]
	global_load_dwordx2 v[60:61], v116, s[10:11] offset:32
	global_load_dwordx2 v[66:67], v118, s[24:25]
	global_load_dwordx2 v[68:69], v118, s[24:25] offset:32
	global_load_dwordx2 v[74:75], v118, s[10:11]
	global_load_dwordx2 v[76:77], v118, s[10:11] offset:32
	global_load_dwordx2 v[82:83], v118, s[16:17]
	global_load_dwordx2 v[84:85], v118, s[16:17] offset:32
	global_load_dwordx2 v[70:71], v120, s[10:11]
	global_load_dwordx2 v[72:73], v120, s[10:11] offset:32
	v_readlane_b32 s10, v255, 39
	v_readlane_b32 s11, v255, 47
	s_add_u32 s10, s10, s11
	v_readlane_b32 s11, v255, 40
	s_addc_u32 s11, s11, 0
	s_add_u32 s2, s2, s10
	s_addc_u32 s3, s3, s11
	v_mov_b32_e32 v117, v1
	v_mov_b32_e32 v119, v1
	v_mov_b32_e32 v121, v1
	v_lshl_add_u64 v[114:115], s[2:3], 0, v[114:115]
	v_lshl_add_u64 v[116:117], s[2:3], 0, v[116:117]
	v_lshl_add_u64 v[118:119], s[2:3], 0, v[118:119]
	v_lshl_add_u64 v[120:121], s[2:3], 0, v[120:121]
	s_add_u32 s2, s10, s6
	s_addc_u32 s3, s11, s7
	s_add_u32 s10, s19, s2
	s_addc_u32 s11, s20, s3
	s_add_u32 s2, s30, s2
	s_addc_u32 s3, s31, s3
	s_add_u32 s2, s2, 0x33920000
	s_addc_u32 s3, s3, 0
	v_mov_b32_e32 v109, v1
	v_mov_b32_e32 v111, v1
	v_mov_b32_e32 v113, v1
	v_mov_b32_e32 v131, v1
	v_mov_b32_e32 v133, v1
	v_mov_b32_e32 v135, v1
	v_mov_b32_e32 v137, v1
	v_mov_b32_e32 v139, v1
	v_mov_b32_e32 v141, v1
	v_mov_b32_e32 v143, v1
	v_mov_b32_e32 v145, v1
	v_mov_b32_e32 v147, v1
	v_mov_b32_e32 v149, v1
	v_mov_b32_e32 v151, v1
	v_mov_b32_e32 v153, v1
	v_lshl_add_u64 v[122:123], s[2:3], 0, v[0:1]
	v_lshl_add_u64 v[124:125], s[2:3], 0, v[108:109]
	v_lshl_add_u64 v[126:127], s[2:3], 0, v[110:111]
	v_lshl_add_u64 v[128:129], s[2:3], 0, v[112:113]
	v_lshl_add_u64 v[130:131], s[2:3], 0, v[130:131]
	v_lshl_add_u64 v[132:133], s[2:3], 0, v[132:133]
	v_lshl_add_u64 v[134:135], s[2:3], 0, v[134:135]
	v_lshl_add_u64 v[136:137], s[2:3], 0, v[136:137]
	v_lshl_add_u64 v[138:139], s[2:3], 0, v[138:139]
	v_lshl_add_u64 v[140:141], s[2:3], 0, v[140:141]
	v_lshl_add_u64 v[142:143], s[2:3], 0, v[142:143]
	v_lshl_add_u64 v[144:145], s[2:3], 0, v[144:145]
	v_lshl_add_u64 v[146:147], s[2:3], 0, v[146:147]
	v_lshl_add_u64 v[148:149], s[2:3], 0, v[148:149]
	v_lshl_add_u64 v[150:151], s[2:3], 0, v[150:151]
	v_lshl_add_u64 v[152:153], s[2:3], 0, v[152:153]
	v_readlane_b32 s2, v254, 56
	s_add_u32 s2, s2, s8
	v_readlane_b32 s3, v254, 57
	s_addc_u32 s3, s3, s9
	s_add_u32 s0, s0, s2
	s_addc_u32 s1, s1, s3
	v_lshlrev_b32_e32 v0, 2, v98
	s_mov_b64 s[2:3], 0x6cb40000
	v_lshl_add_u64 v[156:157], v[0:1], 0, s[2:3]
	v_lshlrev_b32_e32 v0, 2, v100
	v_lshl_add_u64 v[158:159], v[0:1], 0, s[2:3]
	v_lshlrev_b32_e32 v0, 2, v102
	v_lshl_add_u64 v[160:161], v[0:1], 0, s[2:3]
	v_lshlrev_b32_e32 v0, 2, v104
	v_lshl_add_u64 v[162:163], v[0:1], 0, s[2:3]
	v_lshlrev_b32_e32 v0, 2, v106
	v_lshl_add_u64 v[164:165], v[0:1], 0, s[2:3]
	v_lshlrev_b32_e32 v0, 2, v166
	v_lshl_add_u64 v[166:167], v[0:1], 0, s[2:3]
	v_lshlrev_b32_e32 v0, 2, v168
	v_lshl_add_u64 v[168:169], v[0:1], 0, s[2:3]
	v_lshlrev_b32_e32 v0, 2, v170
	v_lshl_add_u64 v[170:171], v[0:1], 0, s[2:3]
	v_lshlrev_b32_e32 v0, 2, v172
	v_lshl_add_u64 v[172:173], v[0:1], 0, s[2:3]
	v_lshlrev_b32_e32 v0, 2, v174
	v_lshl_add_u64 v[174:175], v[0:1], 0, s[2:3]
	v_lshlrev_b32_e32 v0, 2, v176
	v_lshl_add_u64 v[176:177], v[0:1], 0, s[2:3]
	v_lshlrev_b32_e32 v0, 2, v178
	v_lshl_add_u64 v[178:179], v[0:1], 0, s[2:3]
	v_lshlrev_b32_e32 v0, 2, v180
	v_lshl_add_u64 v[180:181], v[0:1], 0, s[2:3]
	v_lshlrev_b32_e32 v0, 2, v182
	v_lshl_add_u64 v[182:183], v[0:1], 0, s[2:3]
	v_lshlrev_b32_e32 v0, 2, v184
	s_mov_b32 s22, 0
	v_or_b32_e32 v154, 0x6cb40000, v154
	v_mov_b32_e32 v155, v1
	v_lshl_add_u64 v[184:185], v[0:1], 0, s[2:3]
	s_mov_b64 s[2:3], 0
	s_waitcnt vmcnt(0)
.LBB0_1498:
	s_waitcnt vmcnt(63)
	v_mfma_f32_16x16x32_bf16 v[54:57], v[94:97], v[2:5], v[54:57]
	v_mov_b32_e32 v220, v186
	v_mov_b32_e32 v0, v187
	v_mfma_f32_16x16x32_bf16 v[54:57], v[90:93], v[6:9], v[54:57]
	v_lshl_add_u64 v[222:223], v[114:115], 0, s[2:3]
	s_mov_b32 s8, 0x5c320000
	s_waitcnt vmcnt(63)
	v_mfma_f32_16x16x32_bf16 v[38:41], v[38:41], v[10:13], v[54:57]
	s_lshl_b32 s12, s18, 2
	s_waitcnt vmcnt(63)
	v_mfma_f32_16x16x32_bf16 v[110:113], v[18:21], v[14:17], v[38:41]
	v_lshl_add_u64 v[18:19], v[122:123], 0, s[2:3]
	global_load_ushort v204, v[18:19], off
	v_lshl_add_u64 v[54:55], s[0:1], 0, v[154:155]
	s_waitcnt vmcnt(27)
	v_mfma_f32_16x16x32_bf16 v[18:21], v[86:89], v[2:5], v[26:29]
	v_lshl_add_u64 v[38:39], s[0:1], 0, v[156:157]
	global_load_dword v54, v[54:55], off
	s_nop 0
	v_mul_f32_e32 v224, v110, v110
	v_mfma_f32_16x16x32_bf16 v[18:21], v[50:53], v[6:9], v[18:21]
	v_lshl_add_u64 v[26:27], v[124:125], 0, s[2:3]
	global_load_ushort v203, v[26:27], off
	global_load_dword v55, v[38:39], off
	s_waitcnt vmcnt(22)
	v_mfma_f32_16x16x32_bf16 v[18:21], v[82:85], v[10:13], v[18:21]
	v_mfma_f32_16x16x32_bf16 v[106:109], v[42:45], v[14:17], v[18:21]
	s_nop 6
	v_lshl_add_u64 v[18:19], v[128:129], 0, s[2:3]
	global_load_ushort v201, v[18:19], off
	v_mfma_f32_16x16x32_bf16 v[18:21], v[78:81], v[2:5], v[30:33]
	v_lshl_add_u64 v[26:27], s[0:1], 0, v[158:159]
	global_load_dword v56, v[26:27], off
	v_lshl_add_u64 v[26:27], v[126:127], 0, s[2:3]
	v_mfma_f32_16x16x32_bf16 v[18:21], v[46:49], v[6:9], v[18:21]
	global_load_ushort v202, v[26:27], off
	v_lshl_add_u64 v[26:27], s[0:1], 0, v[160:161]
	global_load_dword v57, v[26:27], off
	v_mfma_f32_16x16x32_bf16 v[28:31], v[66:69], v[10:13], v[18:21]
	v_add_co_u32_e32 v26, vcc, s8, v222
	s_and_b32 s8, s22, 0x200
	s_nop 0
	v_addc_co_u32_e32 v27, vcc, 0, v223, vcc
	v_mfma_f32_16x16x32_bf16 v[102:105], v[22:25], v[14:17], v[28:31]
	v_lshl_add_u64 v[22:23], v[130:131], 0, s[2:3]
	global_load_dwordx2 v[94:95], v[26:27], off
	global_load_dwordx2 v[96:97], v[26:27], off offset:32
	global_load_dwordx2 v[90:91], v[26:27], off offset:64
	global_load_dwordx2 v[92:93], v[26:27], off offset:96
	global_load_dwordx2 v[38:39], v[26:27], off offset:128
	global_load_dwordx2 v[40:41], v[26:27], off offset:160
	global_load_dwordx2 v[18:19], v[26:27], off offset:192
	global_load_dwordx2 v[20:21], v[26:27], off offset:224
	global_load_ushort v200, v[22:23], off
	v_mfma_f32_16x16x32_bf16 v[22:25], v[62:65], v[2:5], v[34:37]
	v_lshl_add_u64 v[26:27], s[0:1], 0, v[162:163]
	v_lshl_add_u64 v[28:29], s[0:1], 0, v[164:165]
	global_load_dword v26, v[26:27], off
	v_mfma_f32_16x16x32_bf16 v[22:25], v[58:61], v[6:9], v[22:25]
	v_lshl_add_u64 v[58:59], v[116:117], 0, s[2:3]
	global_load_dword v27, v[28:29], off
	v_lshl_add_u64 v[28:29], v[132:133], 0, s[2:3]
	v_mfma_f32_16x16x32_bf16 v[22:25], v[74:77], v[10:13], v[22:25]
	v_lshl_add_u64 v[30:31], v[134:135], 0, s[2:3]
	global_load_ushort v199, v[28:29], off
	global_load_ushort v198, v[30:31], off
	s_waitcnt vmcnt(37)
	v_mfma_f32_16x16x32_bf16 v[98:101], v[70:73], v[14:17], v[22:25]
	v_lshl_add_u64 v[28:29], s[0:1], 0, v[166:167]
	v_lshl_add_u64 v[30:31], s[0:1], 0, v[168:169]
	v_lshl_add_u64 v[70:71], v[118:119], 0, s[2:3]
	v_lshl_add_u64 v[22:23], v[136:137], 0, s[2:3]
	global_load_ushort v197, v[22:23], off
	v_add_co_u32_e32 v22, vcc, s23, v222
	global_load_dword v28, v[28:29], off
	s_nop 0
	v_addc_co_u32_e32 v23, vcc, 0, v223, vcc
	v_add_co_u32_e32 v24, vcc, s23, v58
	global_load_dword v29, v[30:31], off
	s_nop 0
	v_addc_co_u32_e32 v25, vcc, 0, v59, vcc
	global_load_dwordx2 v[86:87], v[22:23], off
	global_load_dwordx2 v[88:89], v[22:23], off offset:32
	global_load_dwordx2 v[50:51], v[24:25], off
	global_load_dwordx2 v[52:53], v[24:25], off offset:32
	v_add_co_u32_e32 v22, vcc, s23, v70
	v_lshl_add_u64 v[72:73], v[120:121], 0, s[2:3]
	s_nop 0
	v_addc_co_u32_e32 v23, vcc, 0, v71, vcc
	v_add_co_u32_e32 v24, vcc, s23, v72
	v_lshl_add_u64 v[36:37], v[146:147], 0, s[2:3]
	s_nop 0
	v_addc_co_u32_e32 v25, vcc, 0, v73, vcc
	global_load_dwordx2 v[82:83], v[22:23], off
	global_load_dwordx2 v[84:85], v[22:23], off offset:32
	global_load_dwordx2 v[42:43], v[24:25], off
	global_load_dwordx2 v[44:45], v[24:25], off offset:32
	v_lshl_add_u64 v[22:23], s[0:1], 0, v[170:171]
	global_load_dword v30, v[22:23], off
	v_lshl_add_u64 v[22:23], v[138:139], 0, s[2:3]
	global_load_ushort v196, v[22:23], off
	v_lshl_add_u64 v[22:23], s[0:1], 0, v[172:173]
	global_load_dword v31, v[22:23], off
	v_lshl_add_u64 v[22:23], v[140:141], 0, s[2:3]
	global_load_ushort v195, v[22:23], off
	v_lshl_add_u64 v[22:23], s[0:1], 0, v[174:175]
	global_load_dword v32, v[22:23], off
	v_lshl_add_u64 v[22:23], v[142:143], 0, s[2:3]
	global_load_ushort v194, v[22:23], off
	v_lshl_add_u64 v[22:23], s[0:1], 0, v[176:177]
	global_load_dword v33, v[22:23], off
	v_lshl_add_u64 v[22:23], v[144:145], 0, s[2:3]
	global_load_ushort v193, v[22:23], off
	v_add_co_u32_e32 v22, vcc, s26, v222
	v_lshl_add_u64 v[60:61], v[150:151], 0, s[2:3]
	s_nop 0
	v_addc_co_u32_e32 v23, vcc, 0, v223, vcc
	v_add_co_u32_e32 v24, vcc, s26, v58
	v_lshl_add_u64 v[34:35], s[0:1], 0, v[178:179]
	s_nop 0
	v_addc_co_u32_e32 v25, vcc, 0, v59, vcc
	global_load_dwordx2 v[78:79], v[22:23], off
	global_load_dwordx2 v[80:81], v[22:23], off offset:32
	global_load_dwordx2 v[46:47], v[24:25], off
	global_load_dwordx2 v[48:49], v[24:25], off offset:32
	v_add_co_u32_e32 v22, vcc, s26, v70
	s_lshl_b32 s8, s8, 2
	s_nop 0
	v_addc_co_u32_e32 v23, vcc, 0, v71, vcc
	v_add_co_u32_e32 v24, vcc, s26, v72
	s_add_i32 s13, s8, 0
	s_nop 0
	v_addc_co_u32_e32 v25, vcc, 0, v73, vcc
	global_load_dwordx2 v[66:67], v[22:23], off
	global_load_dwordx2 v[68:69], v[22:23], off offset:32
	s_nop 0
	global_load_dwordx2 v[22:23], v[24:25], off
	s_nop 0
	global_load_dwordx2 v[24:25], v[24:25], off offset:32
	s_add_i32 s14, s13, s12
	global_load_ushort v192, v[36:37], off
	global_load_ushort v190, v[60:61], off
	v_lshl_add_u64 v[36:37], s[0:1], 0, v[180:181]
	global_load_dword v34, v[34:35], off
	v_lshl_add_u64 v[60:61], s[0:1], 0, v[184:185]
	global_load_dword v35, v[36:37], off
	v_lshl_add_u64 v[36:37], v[148:149], 0, s[2:3]
	global_load_ushort v191, v[36:37], off
	v_lshl_add_u64 v[36:37], s[0:1], 0, v[182:183]
	global_load_dword v36, v[36:37], off
	v_lshl_add_u32 v234, v0, 7, s14
	global_load_dword v37, v[60:61], off
	v_lshl_add_u64 v[60:61], v[152:153], 0, s[2:3]
	global_load_ushort v189, v[60:61], off
	v_add_co_u32_e32 v60, vcc, s27, v222
	v_lshlrev_b32_e32 v222, 2, v220
	s_nop 0
	v_addc_co_u32_e32 v61, vcc, 0, v223, vcc
	v_add_co_u32_e32 v74, vcc, s27, v58
	v_lshl_add_u32 v222, v0, 6, v222
	s_nop 0
	v_addc_co_u32_e32 v75, vcc, 0, v59, vcc
	v_add_co_u32_e32 v70, vcc, s27, v70
	global_load_dwordx2 v[62:63], v[60:61], off
	global_load_dwordx2 v[64:65], v[60:61], off offset:32
	global_load_dwordx2 v[58:59], v[74:75], off
	s_nop 0
	global_load_dwordx2 v[60:61], v[74:75], off offset:32
	v_addc_co_u32_e32 v71, vcc, 0, v71, vcc
	v_add_co_u32_e32 v72, vcc, s27, v72
	v_xor_b32_e32 v223, 4, v222
	s_nop 0
	v_addc_co_u32_e32 v73, vcc, 0, v73, vcc
	global_load_dwordx2 v[74:75], v[70:71], off
	global_load_dwordx2 v[76:77], v[70:71], off offset:32
	s_nop 0
	global_load_dwordx2 v[70:71], v[72:73], off
	s_nop 0
	global_load_dwordx2 v[72:73], v[72:73], off offset:32
	v_xor_b32_e32 v225, 8, v222
	v_xor_b32_e32 v228, 16, v222
	v_xor_b32_e32 v229, 32, v222
	v_cmp_eq_u32_e32 vcc, 0, v220
	v_mul_f32_e32 v222, v110, v110
	v_mul_f32_e32 v224, v111, v111
	v_mul_f32_e32 v226, v112, v112
	ds_bpermute_b32 v250, v223, v222
	ds_bpermute_b32 v251, v223, v224
	ds_bpermute_b32 v252, v223, v226
	s_waitcnt lgkmcnt(0)
	v_fmac_f32_e32 v250, v110, v110
	v_fmac_f32_e32 v251, v111, v111
	v_fmac_f32_e32 v252, v112, v112
	ds_bpermute_b32 v222, v225, v250
	ds_bpermute_b32 v224, v225, v251
	ds_bpermute_b32 v226, v225, v252
	s_waitcnt lgkmcnt(0)
	v_add_f32_e32 v250, v250, v222
	v_add_f32_e32 v251, v251, v224
	v_add_f32_e32 v252, v252, v226
	ds_bpermute_b32 v222, v228, v250
	ds_bpermute_b32 v224, v228, v251
	ds_bpermute_b32 v226, v228, v252
	s_waitcnt lgkmcnt(0)
	v_add_f32_e32 v250, v250, v222
	v_add_f32_e32 v251, v251, v224
	v_add_f32_e32 v252, v252, v226
	ds_bpermute_b32 v222, v229, v250
	ds_bpermute_b32 v224, v229, v251
	ds_bpermute_b32 v226, v229, v252
	s_and_saveexec_b64 s[8:9], vcc
	s_waitcnt lgkmcnt(0)
	v_add_f32_e32 v250, v250, v222
	v_add_f32_e32 v251, v251, v224
	v_add_f32_e32 v252, v252, v226
	ds_write_b32 v234, v250
	ds_write_b32 v234, v251 offset:32
	ds_write_b32 v234, v252 offset:64
	s_or_b64 exec, exec, s[8:9]
	v_mul_f32_e32 v222, v113, v113
	v_mul_f32_e32 v224, v106, v106
	v_mul_f32_e32 v226, v107, v107
	ds_bpermute_b32 v250, v223, v222
	ds_bpermute_b32 v251, v223, v224
	ds_bpermute_b32 v252, v223, v226
	s_waitcnt lgkmcnt(0)
	v_fmac_f32_e32 v250, v113, v113
	v_fmac_f32_e32 v251, v106, v106
	v_fmac_f32_e32 v252, v107, v107
	ds_bpermute_b32 v222, v225, v250
	ds_bpermute_b32 v224, v225, v251
	ds_bpermute_b32 v226, v225, v252
	s_waitcnt lgkmcnt(0)
	v_add_f32_e32 v250, v250, v222
	v_add_f32_e32 v251, v251, v224
	v_add_f32_e32 v252, v252, v226
	ds_bpermute_b32 v222, v228, v250
	ds_bpermute_b32 v224, v228, v251
	ds_bpermute_b32 v226, v228, v252
	s_waitcnt lgkmcnt(0)
	v_add_f32_e32 v250, v250, v222
	v_add_f32_e32 v251, v251, v224
	v_add_f32_e32 v252, v252, v226
	ds_bpermute_b32 v222, v229, v250
	ds_bpermute_b32 v224, v229, v251
	ds_bpermute_b32 v226, v229, v252
	s_and_saveexec_b64 s[8:9], vcc
	s_waitcnt lgkmcnt(0)
	v_add_f32_e32 v250, v250, v222
	v_add_f32_e32 v251, v251, v224
	v_add_f32_e32 v252, v252, v226
	ds_write_b32 v234, v250 offset:96
	ds_write_b32 v234, v251 offset:512
	ds_write_b32 v234, v252 offset:544
	s_or_b64 exec, exec, s[8:9]
	v_mul_f32_e32 v222, v108, v108
	v_mul_f32_e32 v224, v109, v109
	v_mul_f32_e32 v226, v102, v102
	ds_bpermute_b32 v250, v223, v222
	ds_bpermute_b32 v251, v223, v224
	ds_bpermute_b32 v252, v223, v226
	s_waitcnt lgkmcnt(0)
	v_fmac_f32_e32 v250, v108, v108
	v_fmac_f32_e32 v251, v109, v109
	v_fmac_f32_e32 v252, v102, v102
	ds_bpermute_b32 v222, v225, v250
	ds_bpermute_b32 v224, v225, v251
	ds_bpermute_b32 v226, v225, v252
	s_waitcnt lgkmcnt(0)
	v_add_f32_e32 v250, v250, v222
	v_add_f32_e32 v251, v251, v224
	v_add_f32_e32 v252, v252, v226
	ds_bpermute_b32 v222, v228, v250
	ds_bpermute_b32 v224, v228, v251
	ds_bpermute_b32 v226, v228, v252
	s_waitcnt lgkmcnt(0)
	v_add_f32_e32 v250, v250, v222
	v_add_f32_e32 v251, v251, v224
	v_add_f32_e32 v252, v252, v226
	ds_bpermute_b32 v222, v229, v250
	ds_bpermute_b32 v224, v229, v251
	ds_bpermute_b32 v226, v229, v252
	s_and_saveexec_b64 s[8:9], vcc
	s_waitcnt lgkmcnt(0)
	v_add_f32_e32 v250, v250, v222
	v_add_f32_e32 v251, v251, v224
	v_add_f32_e32 v252, v252, v226
	ds_write_b32 v234, v250 offset:576
	ds_write_b32 v234, v251 offset:608
	ds_write_b32 v234, v252 offset:1024
	s_or_b64 exec, exec, s[8:9]
	v_mul_f32_e32 v222, v103, v103
	v_mul_f32_e32 v224, v104, v104
	v_mul_f32_e32 v226, v105, v105
	ds_bpermute_b32 v250, v223, v222
	ds_bpermute_b32 v251, v223, v224
	ds_bpermute_b32 v252, v223, v226
	s_waitcnt lgkmcnt(0)
	v_fmac_f32_e32 v250, v103, v103
	v_fmac_f32_e32 v251, v104, v104
	v_fmac_f32_e32 v252, v105, v105
	ds_bpermute_b32 v222, v225, v250
	ds_bpermute_b32 v224, v225, v251
	ds_bpermute_b32 v226, v225, v252
	s_waitcnt lgkmcnt(0)
	v_add_f32_e32 v250, v250, v222
	v_add_f32_e32 v251, v251, v224
	v_add_f32_e32 v252, v252, v226
	ds_bpermute_b32 v222, v228, v250
	ds_bpermute_b32 v224, v228, v251
	ds_bpermute_b32 v226, v228, v252
	s_waitcnt lgkmcnt(0)
	v_add_f32_e32 v250, v250, v222
	v_add_f32_e32 v251, v251, v224
	v_add_f32_e32 v252, v252, v226
	ds_bpermute_b32 v222, v229, v250
	ds_bpermute_b32 v224, v229, v251
	ds_bpermute_b32 v226, v229, v252
	s_and_saveexec_b64 s[8:9], vcc
	s_waitcnt lgkmcnt(0)
	v_add_f32_e32 v250, v250, v222
	v_add_f32_e32 v251, v251, v224
	v_add_f32_e32 v252, v252, v226
	ds_write_b32 v234, v250 offset:1056
	ds_write_b32 v234, v251 offset:1088
	ds_write_b32 v234, v252 offset:1120
	s_or_b64 exec, exec, s[8:9]
	v_mul_f32_e32 v222, v98, v98
	v_mul_f32_e32 v224, v99, v99
	v_mul_f32_e32 v226, v100, v100
	ds_bpermute_b32 v250, v223, v222
	ds_bpermute_b32 v251, v223, v224
	ds_bpermute_b32 v252, v223, v226
	s_waitcnt lgkmcnt(0)
	v_fmac_f32_e32 v250, v98, v98
	v_fmac_f32_e32 v251, v99, v99
	v_fmac_f32_e32 v252, v100, v100
	ds_bpermute_b32 v222, v225, v250
	ds_bpermute_b32 v224, v225, v251
	ds_bpermute_b32 v226, v225, v252
	s_waitcnt lgkmcnt(0)
	v_add_f32_e32 v250, v250, v222
	v_add_f32_e32 v251, v251, v224
	v_add_f32_e32 v252, v252, v226
	ds_bpermute_b32 v222, v228, v250
	ds_bpermute_b32 v224, v228, v251
	ds_bpermute_b32 v226, v228, v252
	s_waitcnt lgkmcnt(0)
	v_add_f32_e32 v250, v250, v222
	v_add_f32_e32 v251, v251, v224
	v_add_f32_e32 v252, v252, v226
	ds_bpermute_b32 v222, v229, v250
	ds_bpermute_b32 v224, v229, v251
	ds_bpermute_b32 v226, v229, v252
	s_and_saveexec_b64 s[8:9], vcc
	s_waitcnt lgkmcnt(0)
	v_add_f32_e32 v250, v250, v222
	v_add_f32_e32 v251, v251, v224
	v_add_f32_e32 v252, v252, v226
	ds_write_b32 v234, v250 offset:1536
	ds_write_b32 v234, v251 offset:1568
	ds_write_b32 v234, v252 offset:1600
	s_or_b64 exec, exec, s[8:9]
	v_mul_f32_e32 v222, v101, v101
	ds_bpermute_b32 v250, v223, v222
	s_waitcnt lgkmcnt(0)
	v_fmac_f32_e32 v250, v101, v101
	ds_bpermute_b32 v222, v225, v250
	s_waitcnt lgkmcnt(0)
	v_add_f32_e32 v250, v250, v222
	ds_bpermute_b32 v222, v228, v250
	s_waitcnt lgkmcnt(0)
	v_add_f32_e32 v250, v250, v222
	ds_bpermute_b32 v222, v229, v250
	s_and_saveexec_b64 s[8:9], vcc
	s_waitcnt lgkmcnt(0)
	v_add_f32_e32 v250, v250, v222
	ds_write_b32 v234, v250 offset:1632
	s_or_b64 exec, exec, s[8:9]
	v_lshlrev_b32_e32 v222, 2, v0
	v_add_u32_e32 v227, 16, v222
	v_add_u32_e32 v226, 32, v222
	v_add_u32_e32 v224, 48, v222
	v_add_u32_e32 v223, 51, v222
	v_lshlrev_b32_e32 v225, 5, v223
	s_mov_b64 s[8:9], exec
